# k10 + MLA unit prologue: first two K/V tiles requested at the top of the unit
# baseline (speedup 1.0000x reference)
; __device__ __forceinline__ float bf2f(unsigned short h) { return __uint_as_float(((unsigned)h) << 16); }
; #define ATT_LOADG(t, rs) do { const bf16_t* kt_ = Kp + (size_t)(t) * 64 * ldk; const bf16_t* vt_ = VT + (size_t)(t) * 64; \
;     _Pragma("unroll") for (int j = 0; j < NKL; ++j) { const int ci = tid + 512 * j; if (NKC % 512 == 0 || ci < NKC) kreg[rs][j] = *(const u32x4*)(kt_ + kof[j]); } \
;     _Pragma("unroll") for (int j = 0; j < NVL; ++j) vreg[rs][j] = *(const u32x4*)(vt_ + vof[j]); } while (0)
; template <int DQK, int DV, int MODE, int QPRE, bool DIFF> ...
;     ...
;     { const bf16_t* qrow = Q + mp * 256 + (size_t)(q0 + wid * 32 + l32) * ldq + hi * 8;
; #pragma unroll
;       for (int d0 = 0; d0 < ND0; ++d0) qf[d0] = *(const bf16x8*)(qrow + d0 * 16); }
;     if (QPRE != 0) {
;         float v[ND0][8]; float s = 0.f;
; #pragma unroll
;         for (int d0 = 0; d0 < ND0; ++d0)
; #pragma unroll
;             for (int j = 0; j < 8; ++j) { v[d0][j] = bf2f((unsigned short)qf[d0][j]); s += v[d0][j] * v[d0][j]; }
;         { float a, b; swap32(s, a, b); s = a + b; }
;         const float rs = 1.0f / sqrtf(s * (1.0f / DQK) + EPS);
; #pragma unroll
;         for (int d0 = 0; d0 < ND0; ++d0) { const f32x4 g0 = *(const f32x4*)(qg + d0 * 16 + hi * 8), g1 = *(const f32x4*)(qg + d0 * 16 + hi * 8 + 4);
; #pragma unroll
;             for (int j = 0; j < 4; ++j) { v[d0][j] *= rs * c * g0[j]; v[d0][4 + j] *= rs * c * g1[j]; } }
;         if (QPRE == 3) {
;             const int pos = q0 + wid * 32 + l32;
; #pragma unroll
;             for (int j = 0; j < 8; ++j) { float cs, sn; rope_cs(pos, 2 * (8 * hi + j), cs, sn); const float x1 = v[ND0 - 2][j], x2 = v[ND0 - 1][j];
;     ...
;     unsigned kof[NKL], vof[NVL];
; #pragma unroll
;     for (int j = 0; j < NKL; ++j) { const int ci = tid + 512 * j; const int row = ci / KCH, cc = ci % KCH; kof[j] = (unsigned)(row * ldk + cc * 8); }
; #pragma unroll
;     for (int j = 0; j < NVL; ++j) { const int ci = tid + 512 * j; const int d = ci >> 3, cc = ci & 7; vof[j] = (unsigned)(d * ldvt + cc * 8); }
;     ...
;     ATT_LOADG(ATT_TILE(0), 0); if (DEEP) { ATT_LOADG(ATT_TILE(1), (DEEP ? 1 : 0)); ATT_LOADG(ATT_TILE(2), (DEEP ? 2 : 0)); ATT_LOADG(ATT_TILE(3), (DEEP ? 3 : 0)); }
.LBB0_1637:
	s_ashr_i32 s4, s2, 7
	s_sub_i32 s27, 15, s4
	s_lshl_b32 s4, s2, 8
	s_and_b32 s52, s4, 0x7000
	s_and_b32 s53, s2, 15
	s_mul_i32 s6, s52, 0xc00
	s_add_u32 s4, s0, s6
	s_addc_u32 s5, s1, 0
	s_mul_i32 s26, s53, 0xc0
	s_add_u32 s4, s4, s26
	s_addc_u32 s5, s5, 0
	s_add_u32 s6, s3, s6
	s_addc_u32 s7, s28, 0
	v_mbcnt_lo_u32_b32 v167, -1, 0
	v_mbcnt_hi_u32_b32 v167, -1, v167
	s_add_u32 s10, s6, s26
	v_ashrrev_i32_e32 v182, 5, v167
	v_lshlrev_b32_e32 v170, 4, v182
	s_addc_u32 s11, s7, 0
	v_add_u32_e32 v244, s35, v167
	v_mul_hi_i32 v245, v244, s40
	v_lshrrev_b32_e32 v246, 31, v245
	v_ashrrev_i32_e32 v245, 1, v245
	v_add_u32_e32 v245, v245, v246
	v_mul_lo_u32 v246, v245, 12
	v_sub_u32_e32 v246, v244, v246
	v_mul_lo_u32 v245, v245, s41
	v_lshl_add_u32 v245, v246, 3, v245
	v_lshlrev_b32_e32 v245, 1, v245
	v_add_u32_e32 v247, 0x200, v244
	v_mul_hi_i32 v248, v247, s40
	v_lshrrev_b32_e32 v249, 31, v248
	v_ashrrev_i32_e32 v248, 1, v248
	v_add_u32_e32 v248, v248, v249
	v_mul_lo_u32 v249, v248, 12
	v_sub_u32_e32 v249, v247, v249
	v_mul_lo_u32 v248, v248, s41
	v_lshl_add_u32 v248, v249, 3, v248
	v_lshlrev_b32_e32 v248, 1, v248
	v_lshlrev_b32_e32 v250, 12, v244
	v_and_b32_e32 v250, 0xffff8000, v250
	v_lshlrev_b32_e32 v251, 3, v167
	v_and_b32_e32 v251, 56, v251
	v_or_b32_e32 v250, v250, v251
	v_lshlrev_b32_e32 v250, 1, v250
	s_lshl_b32 s98, s53, 22
	s_add_u32 s100, s29, s98
	s_addc_u32 s101, s30, 0
	s_lshl_b32 s98, s52, 1
	s_add_u32 s100, s100, s98
	s_addc_u32 s101, s101, 0
	s_add_u32 s98, s10, 0x30000
	s_addc_u32 s99, s11, 0
	global_load_dwordx4 v[220:223], v245, s[10:11]
	global_load_dwordx4 v[228:231], v250, s[100:101]
	global_load_dwordx4 v[232:235], v245, s[98:99]
	global_load_dwordx4 v[240:243], v250, s[100:101] offset:128
	s_cmp_lt_u32 s35, 0x100
	s_cbranch_scc0 .Lmla_kv_skip
	global_load_dwordx4 v[224:227], v248, s[10:11]
	global_load_dwordx4 v[236:239], v248, s[98:99]
.Lmla_kv_skip:
	v_ashrrev_i32_e32 v171, 31, v170
	v_lshlrev_b64 v[82:83], 3, v[170:171]
	s_getpc_b64 s[6:7]
	s_add_u32 s6, s6, _ZL8ROPE_REV@rel32@lo+4
	s_addc_u32 s7, s7, _ZL8ROPE_REV@rel32@hi+12
	s_waitcnt lgkmcnt(0)
	v_lshl_add_u64 v[0:1], s[6:7], 0, v[82:83]
	global_load_dwordx2 v[204:205], v[0:1], off
	global_load_dwordx2 v[206:207], v[0:1], off offset:16
	global_load_dwordx2 v[208:209], v[0:1], off offset:32
	global_load_dwordx2 v[210:211], v[0:1], off offset:48
	global_load_dwordx2 v[212:213], v[0:1], off offset:64
	global_load_dwordx2 v[214:215], v[0:1], off offset:80
	global_load_dwordx2 v[216:217], v[0:1], off offset:96
	global_load_dwordx2 v[218:219], v[0:1], off offset:112
	s_lshl_b32 s56, s27, 8
	v_mov_b64_e32 v[50:51], s[4:5]
	s_getpc_b64 s[4:5]
	s_add_u32 s4, s4, _ZL8ROPE_REV@rel32@lo+20
	s_addc_u32 s5, s5, _ZL8ROPE_REV@rel32@hi+28
	v_and_b32_e32 v166, 31, v167
	s_add_i32 s56, s56, s36
	v_or_b32_e32 v168, s56, v166
	v_cvt_f64_u32_e32 v[80:81], v168
	v_lshlrev_b32_e32 v48, 3, v182
	v_ashrrev_i32_e32 v49, 31, v48
	v_lshl_add_u64 v[76:77], s[4:5], 0, v[82:83]
	v_mad_u64_u32 v[50:51], s[4:5], v168, s39, v[50:51]
	v_lshl_add_u64 v[4:5], v[48:49], 2, s[16:17]
	v_lshl_add_u64 v[64:65], v[48:49], 1, v[50:51]
	global_load_dwordx4 v[40:43], v[4:5], off offset:16
	global_load_dwordx4 v[44:47], v[4:5], off
	global_load_dwordx4 v[32:35], v[4:5], off offset:80
	global_load_dwordx4 v[36:39], v[4:5], off offset:64
	global_load_dwordx4 v[24:27], v[4:5], off offset:144
	global_load_dwordx4 v[28:31], v[4:5], off offset:128
	global_load_dwordx4 v[16:19], v[4:5], off offset:208
	global_load_dwordx4 v[20:23], v[4:5], off offset:192
	global_load_dwordx4 v[8:11], v[4:5], off offset:272
	global_load_dwordx4 v[12:15], v[4:5], off offset:256
	global_load_dwordx4 v[0:3], v[4:5], off offset:336
	s_nop 0
	global_load_dwordx4 v[4:7], v[4:5], off offset:320
	s_nop 0
	global_load_dwordx4 v[48:51], v[64:65], off
	global_load_dwordx4 v[52:55], v[64:65], off offset:32
	s_getpc_b64 s[4:5]
	s_add_u32 s4, s4, _ZL8ROPE_REV@rel32@lo+36
	s_addc_u32 s5, s5, _ZL8ROPE_REV@rel32@hi+44
	v_add_u32_e32 v172, s35, v167
	v_cmp_gt_i32_e64 s[6:7], s42, v172
	s_waitcnt vmcnt(0)
	v_mul_f64 v[58:59], v[204:205], v[80:81]
	v_rndne_f64_e32 v[58:59], v[58:59]
	v_fma_f64 v[56:57], v[204:205], v[80:81], -v[58:59]
	v_cvt_f32_f64_e32 v56, v[56:57]
	v_cos_f32_e32 v74, v56
	v_sin_f32_e32 v72, v56
	global_load_dwordx4 v[56:59], v[64:65], off offset:64
	global_load_dwordx4 v[60:63], v[64:65], off offset:96
	global_load_dwordx4 v[68:71], v[64:65], off offset:128
	s_nop 0
	global_load_dwordx4 v[64:67], v[64:65], off offset:160
	v_and_b32_e32 v163, 0xffff0000, v48
	v_and_b32_e32 v151, 0xffff0000, v55
	v_lshlrev_b32_e32 v150, 16, v55
	v_and_b32_e32 v157, 0xffff0000, v54
	v_lshlrev_b32_e32 v156, 16, v54
	v_lshlrev_b32_e32 v162, 16, v48
	v_mul_f32_e32 v48, v163, v163
	v_and_b32_e32 v159, 0xffff0000, v51
	v_lshlrev_b32_e32 v158, 16, v51
	v_and_b32_e32 v161, 0xffff0000, v50
	v_lshlrev_b32_e32 v160, 16, v50
	v_and_b32_e32 v51, 0xffff0000, v49
	v_lshlrev_b32_e32 v50, 16, v49
	v_pk_fma_f32 v[48:49], v[162:163], v[162:163], v[48:49] op_sel_hi:[1,1,0]
	v_mul_f32_e32 v88, v159, v159
	v_pk_fma_f32 v[48:49], v[50:51], v[50:51], v[48:49]
	v_and_b32_e32 v155, 0xffff0000, v53
	v_lshlrev_b32_e32 v154, 16, v53
	v_and_b32_e32 v53, 0xffff0000, v52
	v_lshlrev_b32_e32 v52, 16, v52
	v_mul_f32_e32 v90, v53, v53
	v_mul_f32_e32 v92, v155, v155
	v_mul_f32_e32 v94, v157, v157
	v_mul_f32_e32 v96, v151, v151
	s_waitcnt vmcnt(3)
	v_and_b32_e32 v149, 0xffff0000, v56
	v_lshlrev_b32_e32 v148, 16, v56
	v_mul_f32_e32 v98, v149, v149
	v_and_b32_e32 v145, 0xffff0000, v59
	v_lshlrev_b32_e32 v144, 16, v59
	s_waitcnt vmcnt(0)
; __device__ __forceinline__ float bf2f(unsigned short h) { return __uint_as_float(((unsigned)h) << 16); }
; template <int DQK, int DV, int MODE, int QPRE, bool DIFF> ...
;     ...
;         float v[ND0][8]; float s = 0.f;
; #pragma unroll
;         for (int d0 = 0; d0 < ND0; ++d0)
; #pragma unroll
;             for (int j = 0; j < 8; ++j) { v[d0][j] = bf2f((unsigned short)qf[d0][j]); s += v[d0][j] * v[d0][j]; }
;         { float a, b; swap32(s, a, b); s = a + b; }
;         const float rs = 1.0f / sqrtf(s * (1.0f / DQK) + EPS);
; #pragma unroll
;         for (int d0 = 0; d0 < ND0; ++d0) { const f32x4 g0 = *(const f32x4*)(qg + d0 * 16 + hi * 8), g1 = *(const f32x4*)(qg + d0 * 16 + hi * 8 + 4);
; #pragma unroll
;             for (int j = 0; j < 4; ++j) { v[d0][j] *= rs * c * g0[j]; v[d0][4 + j] *= rs * c * g1[j]; } }
;         if (QPRE == 3) {
;             const int pos = q0 + wid * 32 + l32;
; #pragma unroll
;             for (int j = 0; j < 8; ++j) { float cs, sn; rope_cs(pos, 2 * (8 * hi + j), cs, sn); const float x1 = v[ND0 - 2][j], x2 = v[ND0 - 1][j];
	v_mul_f64 v[78:79], v[206:207], v[80:81]
	v_rndne_f64_e32 v[78:79], v[78:79]
	v_fma_f64 v[76:77], v[206:207], v[80:81], -v[78:79]
	v_cvt_f32_f64_e32 v73, v[76:77]
	v_cos_f32_e32 v75, v73
	v_sin_f32_e32 v73, v73
	v_lshl_add_u64 v[76:77], s[4:5], 0, v[82:83]
	s_getpc_b64 s[4:5]
	s_add_u32 s4, s4, _ZL8ROPE_REV@rel32@lo+52
	s_addc_u32 s5, s5, _ZL8ROPE_REV@rel32@hi+60
	v_lshl_add_u64 v[84:85], s[4:5], 0, v[82:83]
	s_getpc_b64 s[4:5]
	s_add_u32 s4, s4, _ZL8ROPE_REV@rel32@lo+68
	s_addc_u32 s5, s5, _ZL8ROPE_REV@rel32@hi+76
	v_and_b32_e32 v147, 0xffff0000, v58
	v_lshlrev_b32_e32 v146, 16, v58
	v_and_b32_e32 v59, 0xffff0000, v57
	v_lshlrev_b32_e32 v58, 16, v57
	v_mul_f32_e32 v100, v59, v59
	v_mul_f32_e32 v102, v147, v147
	v_mul_f32_e32 v104, v145, v145
	v_and_b32_e32 v141, 0xffff0000, v63
	v_lshlrev_b32_e32 v140, 16, v63
	v_and_b32_e32 v143, 0xffff0000, v62
	v_lshlrev_b32_e32 v142, 16, v62
	v_and_b32_e32 v63, 0xffff0000, v61
	v_lshlrev_b32_e32 v62, 16, v61
	v_and_b32_e32 v61, 0xffff0000, v60
	v_lshlrev_b32_e32 v60, 16, v60
	v_mul_f32_e32 v106, v61, v61
	v_mul_f32_e32 v108, v63, v63
	v_mul_f32_e32 v110, v143, v143
	v_mul_f32_e32 v112, v141, v141
	v_and_b32_e32 v139, 0xffff0000, v69
	v_lshlrev_b32_e32 v138, 16, v69
	v_and_b32_e32 v69, 0xffff0000, v68
	v_lshlrev_b32_e32 v68, 16, v68
	v_mul_f32_e32 v114, v69, v69
	v_mul_f32_e32 v116, v139, v139
	v_and_b32_e32 v137, 0xffff0000, v70
	v_lshlrev_b32_e32 v136, 16, v70
	v_mul_f32_e32 v118, v137, v137
	v_and_b32_e32 v135, 0xffff0000, v71
	v_lshlrev_b32_e32 v134, 16, v71
	v_mul_f32_e32 v120, v135, v135
	v_and_b32_e32 v71, 0xffff0000, v65
	v_lshlrev_b32_e32 v70, 16, v65
	v_and_b32_e32 v65, 0xffff0000, v64
	v_lshlrev_b32_e32 v64, 16, v64
	v_mul_f32_e32 v122, v65, v65
	v_mul_f32_e32 v124, v71, v71
	v_and_b32_e32 v133, 0xffff0000, v67
	v_lshlrev_b32_e32 v132, 16, v67
	v_and_b32_e32 v67, 0xffff0000, v66
	v_lshlrev_b32_e32 v66, 16, v66
	v_mul_f32_e32 v126, v67, v67
	v_mul_f32_e32 v164, v133, v133
	s_waitcnt vmcnt(0)
	v_mul_f64 v[78:79], v[208:209], v[80:81]
	v_rndne_f64_e32 v[78:79], v[78:79]
	v_fma_f64 v[76:77], v[208:209], v[80:81], -v[78:79]
	v_cvt_f32_f64_e32 v76, v[76:77]
	v_cos_f32_e32 v78, v76
	v_sin_f32_e32 v76, v76
	s_waitcnt vmcnt(0)
	v_mul_f64 v[86:87], v[210:211], v[80:81]
	v_rndne_f64_e32 v[86:87], v[86:87]
	v_fma_f64 v[84:85], v[210:211], v[80:81], -v[86:87]
	v_cvt_f32_f64_e32 v77, v[84:85]
	v_cos_f32_e32 v79, v77
	v_sin_f32_e32 v77, v77
	v_lshl_add_u64 v[84:85], s[4:5], 0, v[82:83]
	s_getpc_b64 s[4:5]
	s_add_u32 s4, s4, _ZL8ROPE_REV@rel32@lo+84
	s_addc_u32 s5, s5, _ZL8ROPE_REV@rel32@hi+92
	s_waitcnt vmcnt(0)
	v_mul_f64 v[86:87], v[212:213], v[80:81]
	v_rndne_f64_e32 v[86:87], v[86:87]
	v_fma_f64 v[84:85], v[212:213], v[80:81], -v[86:87]
	v_cvt_f32_f64_e32 v84, v[84:85]
	v_cos_f32_e32 v130, v84
	v_sin_f32_e32 v128, v84
	v_lshl_add_u64 v[84:85], s[4:5], 0, v[82:83]
	s_getpc_b64 s[4:5]
	s_add_u32 s4, s4, _ZL8ROPE_REV@rel32@lo+100
	s_addc_u32 s5, s5, _ZL8ROPE_REV@rel32@hi+108
	s_waitcnt vmcnt(0)
	v_mul_f64 v[86:87], v[214:215], v[80:81]
	v_rndne_f64_e32 v[86:87], v[86:87]
	v_fma_f64 v[84:85], v[214:215], v[80:81], -v[86:87]
	v_cvt_f32_f64_e32 v84, v[84:85]
	v_cos_f32_e32 v131, v84
	v_sin_f32_e32 v129, v84
	v_lshl_add_u64 v[84:85], s[4:5], 0, v[82:83]
	s_getpc_b64 s[4:5]
	s_add_u32 s4, s4, _ZL8ROPE_REV@rel32@lo+116
	s_addc_u32 s5, s5, _ZL8ROPE_REV@rel32@hi+124
	v_lshl_add_u64 v[82:83], s[4:5], 0, v[82:83]
	v_mul_hi_i32 v86, v172, s40
	v_lshrrev_b32_e32 v87, 31, v86
	v_ashrrev_i32_e32 v86, 1, v86
	v_add_u32_e32 v171, v86, v87
	v_mul_lo_u32 v86, v171, 12
	v_mul_lo_u32 v87, v171, s41
	v_sub_u32_e32 v174, v172, v86
	v_mul_f32_e32 v86, v161, v161
	v_lshl_add_u32 v152, v174, 3, v87
	s_waitcnt vmcnt(0)
; __device__ __forceinline__ float bf2f(unsigned short h) { return __uint_as_float(((unsigned)h) << 16); }
; template <int DQK, int DV, int MODE, int QPRE, bool DIFF> ...
;     ...
;         for (int d0 = 0; d0 < ND0; ++d0)
; #pragma unroll
;             for (int j = 0; j < 8; ++j) { v[d0][j] = bf2f((unsigned short)qf[d0][j]); s += v[d0][j] * v[d0][j]; }
;         { float a, b; swap32(s, a, b); s = a + b; }
;         const float rs = 1.0f / sqrtf(s * (1.0f / DQK) + EPS);
; #pragma unroll
;         for (int d0 = 0; d0 < ND0; ++d0) { const f32x4 g0 = *(const f32x4*)(qg + d0 * 16 + hi * 8), g1 = *(const f32x4*)(qg + d0 * 16 + hi * 8 + 4);
; #pragma unroll
;             for (int j = 0; j < 4; ++j) { v[d0][j] *= rs * c * g0[j]; v[d0][4 + j] *= rs * c * g1[j]; } }
;         if (QPRE == 3) {
;             const int pos = q0 + wid * 32 + l32;
; #pragma unroll
;             for (int j = 0; j < 8; ++j) { float cs, sn; rope_cs(pos, 2 * (8 * hi + j), cs, sn); const float x1 = v[ND0 - 2][j], x2 = v[ND0 - 1][j];
	v_mul_f64 v[54:55], v[216:217], v[80:81]
	v_rndne_f64_e32 v[54:55], v[54:55]
	v_fma_f64 v[54:55], v[216:217], v[80:81], -v[54:55]
	v_cvt_f32_f64_e32 v54, v[54:55]
	v_cos_f32_e32 v56, v54
	v_sin_f32_e32 v54, v54
	v_mul_f32_e32 v84, v51, v51
	v_pk_add_f32 v[48:49], v[84:85], v[48:49] op_sel_hi:[0,1]
	v_pk_fma_f32 v[48:49], v[160:161], v[160:161], v[48:49]
	s_nop 0
	v_pk_add_f32 v[48:49], v[86:87], v[48:49] op_sel_hi:[0,1]
	v_pk_fma_f32 v[48:49], v[158:159], v[158:159], v[48:49]
	s_nop 0
	v_pk_add_f32 v[48:49], v[88:89], v[48:49] op_sel_hi:[0,1]
	v_pk_fma_f32 v[48:49], v[52:53], v[52:53], v[48:49]
	s_nop 0
	v_pk_add_f32 v[48:49], v[90:91], v[48:49] op_sel_hi:[0,1]
	v_pk_fma_f32 v[48:49], v[154:155], v[154:155], v[48:49]
	s_nop 0
	v_pk_add_f32 v[48:49], v[92:93], v[48:49] op_sel_hi:[0,1]
	v_pk_fma_f32 v[48:49], v[156:157], v[156:157], v[48:49]
	s_nop 0
	v_pk_add_f32 v[48:49], v[94:95], v[48:49] op_sel_hi:[0,1]
	v_pk_fma_f32 v[48:49], v[150:151], v[150:151], v[48:49]
	s_nop 0
	v_pk_add_f32 v[48:49], v[96:97], v[48:49] op_sel_hi:[0,1]
	v_pk_fma_f32 v[48:49], v[148:149], v[148:149], v[48:49]
	s_nop 0
	v_pk_add_f32 v[48:49], v[98:99], v[48:49] op_sel_hi:[0,1]
	v_pk_fma_f32 v[48:49], v[58:59], v[58:59], v[48:49]
	s_nop 0
	v_pk_add_f32 v[48:49], v[100:101], v[48:49] op_sel_hi:[0,1]
	v_pk_fma_f32 v[48:49], v[146:147], v[146:147], v[48:49]
	s_nop 0
	v_pk_add_f32 v[48:49], v[102:103], v[48:49] op_sel_hi:[0,1]
	v_pk_fma_f32 v[48:49], v[144:145], v[144:145], v[48:49]
	s_nop 0
	v_pk_add_f32 v[48:49], v[104:105], v[48:49] op_sel_hi:[0,1]
	v_pk_fma_f32 v[48:49], v[60:61], v[60:61], v[48:49]
	s_nop 0
	v_pk_add_f32 v[48:49], v[106:107], v[48:49] op_sel_hi:[0,1]
	v_pk_fma_f32 v[48:49], v[62:63], v[62:63], v[48:49]
	s_nop 0
	v_pk_add_f32 v[48:49], v[108:109], v[48:49] op_sel_hi:[0,1]
	v_pk_fma_f32 v[48:49], v[142:143], v[142:143], v[48:49]
	s_nop 0
	v_pk_add_f32 v[48:49], v[110:111], v[48:49] op_sel_hi:[0,1]
	v_pk_fma_f32 v[48:49], v[140:141], v[140:141], v[48:49]
	s_nop 0
	v_pk_add_f32 v[48:49], v[112:113], v[48:49] op_sel_hi:[0,1]
	v_pk_fma_f32 v[48:49], v[68:69], v[68:69], v[48:49]
	s_nop 0
	v_pk_add_f32 v[48:49], v[114:115], v[48:49] op_sel_hi:[0,1]
	v_pk_fma_f32 v[48:49], v[138:139], v[138:139], v[48:49]
	s_nop 0
	v_pk_add_f32 v[48:49], v[116:117], v[48:49] op_sel_hi:[0,1]
	v_pk_fma_f32 v[48:49], v[136:137], v[136:137], v[48:49]
	s_nop 0
	v_pk_add_f32 v[48:49], v[118:119], v[48:49] op_sel_hi:[0,1]
	v_pk_fma_f32 v[48:49], v[134:135], v[134:135], v[48:49]
	s_nop 0
	v_pk_add_f32 v[48:49], v[120:121], v[48:49] op_sel_hi:[0,1]
	v_pk_fma_f32 v[48:49], v[64:65], v[64:65], v[48:49]
	s_nop 0
	v_pk_add_f32 v[48:49], v[122:123], v[48:49] op_sel_hi:[0,1]
	v_pk_fma_f32 v[48:49], v[70:71], v[70:71], v[48:49]
	s_nop 0
	v_pk_add_f32 v[48:49], v[124:125], v[48:49] op_sel_hi:[0,1]
	v_pk_fma_f32 v[48:49], v[66:67], v[66:67], v[48:49]
	s_nop 0
	v_pk_add_f32 v[48:49], v[126:127], v[48:49] op_sel_hi:[0,1]
	v_pk_fma_f32 v[48:49], v[132:133], v[132:133], v[48:49]
	s_nop 0
	v_pk_add_f32 v[164:165], v[164:165], v[48:49] op_sel_hi:[0,1]
	v_mov_b32_e32 v177, v164
	s_nop 1
	v_permlane32_swap_b32_e32 v164, v177
	s_waitcnt vmcnt(0)
	v_mul_f64 v[48:49], v[218:219], v[80:81]
	v_rndne_f64_e32 v[48:49], v[48:49]
	v_fma_f64 v[48:49], v[218:219], v[80:81], -v[48:49]
	v_cvt_f32_f64_e32 v48, v[48:49]
	v_cos_f32_e32 v57, v48
	v_sin_f32_e32 v55, v48
	s_and_saveexec_b64 s[8:9], s[6:7]
	s_cbranch_execz .LBB0_1639
	v_mov_b32_e32 v153, v169
	v_lshl_add_u64 v[48:49], v[152:153], 1, s[10:11]

.LBB0_1641:
	s_or_b64 exec, exec, s[22:23]
	s_lshl_b32 s58, s53, 22
	s_add_u32 s4, s29, s58
	s_addc_u32 s5, s30, 0
	s_lshl_b32 s22, s52, 1
	v_lshlrev_b32_e32 v49, 12, v172
	v_lshlrev_b32_e32 v179, 3, v167
	s_add_u32 s4, s4, s22
	v_and_b32_e32 v165, 0xffff8000, v49
	v_and_b32_e32 v176, 56, v179
	s_addc_u32 s5, s5, 0
	v_or_b32_e32 v88, v165, v176
	v_mov_b32_e32 v89, v169
	v_lshl_add_u64 v[124:125], v[88:89], 1, s[4:5]
	s_add_u32 s22, s10, 0x30000
	s_addc_u32 s23, s11, 0
	s_and_saveexec_b64 s[24:25], s[6:7]
	s_cbranch_execz .LBB0_1643
	v_mov_b32_e32 v153, v169
	v_lshl_add_u64 v[88:89], v[152:153], 1, s[22:23]

.LBB0_1645:
	s_or_b64 exec, exec, s[24:25]
	s_add_u32 s22, s10, 0x60000
	s_addc_u32 s23, s11, 0
	s_and_saveexec_b64 s[24:25], s[6:7]
	s_cbranch_execz .LBB0_1647
	v_mov_b32_e32 v153, v169
	v_lshl_add_u64 v[100:101], v[152:153], 1, s[22:23]
	global_load_dwordx4 v[100:103], v[100:101], off

.LBB0_1653:
	s_or_b64 exec, exec, s[22:23]
	global_load_dwordx4 v[124:127], v[124:125], off offset:384
	v_mul_lo_u32 v173, v171, s46
	v_lshlrev_b32_e32 v171, 4, v174
	v_add3_u32 v49, 0, v173, v171
	s_and_saveexec_b64 s[4:5], s[6:7]
	s_cbranch_execz .LBB0_1655
	ds_write_b128 v49, v[220:223]
.LBB0_1655:
	s_or_b64 exec, exec, s[4:5]
	v_mul_lo_u32 v174, v175, s46
	v_lshlrev_b32_e32 v183, 4, v178
	s_and_saveexec_b64 s[10:11], s[8:9]
	s_cbranch_execz .LBB0_1657
	v_lshlrev_b32_e32 v153, 4, v178
	v_add3_u32 v153, 0, v174, v153
	ds_write_b128 v153, v[224:227]
.LBB0_1657:
	s_or_b64 exec, exec, s[10:11]
	v_lshrrev_b32_e32 v153, 3, v172
	v_mul_lo_u32 v172, v153, s47
	v_lshlrev_b32_e32 v153, 4, v167
	v_and_b32_e32 v175, 0x60, v153
	v_add3_u32 v153, 0, v172, v175
	v_and_b32_e32 v167, 8, v179
	v_add_u32_e32 v184, v153, v167
	v_add_u32_e32 v185, 0x3000, v184
	ds_write2_b64 v185, v[228:229], v[230:231] offset0:128 offset1:130
	s_and_saveexec_b64 s[4:5], s[6:7]
	s_cbranch_execnz .LBB0_1725
	s_or_b64 exec, exec, s[4:5]
	s_and_saveexec_b64 s[4:5], vcc
	s_xor_b64 s[4:5], exec, s[4:5]
	s_cbranch_execnz .LBB0_1726

; template <int DQK, int DV, int MODE, int QPRE, bool DIFF> ...
;     ...
;         const float rs = 1.0f / sqrtf(s * (1.0f / DQK) + EPS);
.LBB0_1660:
	v_add3_u32 v49, 0, v174, v183
	ds_write_b128 v49, v[236:239] offset:22528
.LBB0_1661:
	s_or_b64 exec, exec, s[10:11]
	v_add_f32_e32 v49, v164, v177
	v_fmamk_f32 v49, v49, 0x3c2aaaab, v180
	v_mul_f32_e32 v153, 0x4f800000, v49
	v_cmp_gt_f32_e32 vcc, s48, v49
	s_lshl_b32 s54, s27, 2
	s_lshl_b32 s53, s53, 6
	v_cndmask_b32_e32 v49, v49, v153, vcc
	v_sqrt_f32_e32 v153, v49
	s_add_i32 s55, s54, 4
	s_lshr_b32 s56, s56, 6
	v_add_u32_e32 v186, 0x8800, v184
	v_add_u32_e32 v164, -1, v153
	v_fma_f32 v177, -v164, v153, v49
	v_cmp_ge_f32_e64 s[10:11], 0, v177
	v_add_u32_e32 v177, 1, v153
	v_add_u32_e32 v188, 0, v173
	v_cndmask_b32_e64 v164, v153, v164, s[10:11]
	v_fma_f32 v153, -v177, v153, v49
	v_cmp_lt_f32_e64 s[10:11], 0, v153
	v_add_u32_e32 v189, 0, v174
	ds_write2_b64 v186, v[240:241], v[242:243] offset0:128 offset1:130
	v_cndmask_b32_e64 v153, v164, v177, s[10:11]
	v_mul_f32_e32 v164, 0x37800000, v153
	v_cndmask_b32_e32 v153, v153, v164, vcc
	v_cmp_class_f32_e32 vcc, v49, v181
	v_mad_u32_u24 v187, v166, s47, 0
	s_waitcnt lgkmcnt(0)
	s_barrier
; __device__ __forceinline__ unsigned cvtpk(float lo, float hi) { f32x2_t v = {lo, hi}; bf16x2_t b = __builtin_convertvector(v, bf16x2_t); return __builtin_bit_cast(unsigned, b); }
; template <int DQK, int DV, int MODE, int QPRE, bool DIFF> ...
;     ...
;         const float rs = 1.0f / sqrtf(s * (1.0f / DQK) + EPS);
; #pragma unroll
;         for (int d0 = 0; d0 < ND0; ++d0) { const f32x4 g0 = *(const f32x4*)(qg + d0 * 16 + hi * 8), g1 = *(const f32x4*)(qg + d0 * 16 + hi * 8 + 4);
; #pragma unroll
;             for (int j = 0; j < 4; ++j) { v[d0][j] *= rs * c * g0[j]; v[d0][4 + j] *= rs * c * g1[j]; } }
;         if (QPRE == 3) {
;             const int pos = q0 + wid * 32 + l32;
; #pragma unroll
;             for (int j = 0; j < 8; ++j) { float cs, sn; rope_cs(pos, 2 * (8 * hi + j), cs, sn); const float x1 = v[ND0 - 2][j], x2 = v[ND0 - 1][j];
;                 v[ND0 - 2][j] = x1 * cs - x2 * sn; v[ND0 - 1][j] = x1 * sn + x2 * cs; }
;         }
; #pragma unroll
;         for (int d0 = 0; d0 < ND0; ++d0) { u32x4 w; w.x = cvtpk(v[d0][0], v[d0][1]); w.y = cvtpk(v[d0][2], v[d0][3]); w.z = cvtpk(v[d0][4], v[d0][5]); w.w = cvtpk(v[d0][6], v[d0][7]); qf[d0] = __builtin_bit_cast(bf16x8, w); }
;     }
;     f32x16 o[NDB];
; #pragma unroll
;     for (int i = 0; i < NDB; ++i)
; #pragma unroll
;         for (int r = 0; r < 16; ++r) o[i][r] = 0.f;
;     float mhat = 0.f, l_run = 0.f, Rp = 1.0f;
;     bool sb_done = false;
;     f32x16 negm;
; #pragma unroll
;     for (int r = 0; r < 16; ++r) negm[r] = 0.f;
	v_cndmask_b32_e32 v49, v153, v49, vcc
	v_div_scale_f32 v153, s[4:5], v49, v49, 1.0
	v_rcp_f32_e32 v164, v153
	s_bfe_u32 s4, s2, 0x30004
	s_mul_i32 s4, s4, 0xc00000
	s_or_b32 s4, s4, s26
	v_fma_f32 v177, -v153, v164, 1.0
	v_fmac_f32_e32 v164, v177, v164
	v_div_scale_f32 v177, vcc, 1.0, v49, 1.0
	v_mul_f32_e32 v178, v177, v164
	v_fma_f32 v179, -v153, v178, v177
	v_fmac_f32_e32 v178, v179, v164
	v_fma_f32 v153, -v153, v178, v177
	v_div_fmas_f32 v153, v153, v164, v178
	v_div_fixup_f32 v49, v153, v49, 1.0
	v_mul_f32_e32 v164, 0x3e16c740, v49
	v_pk_mul_f32 v[4:5], v[164:165], v[4:5] op_sel_hi:[0,1]
	v_pk_mul_f32 v[46:47], v[46:47], v[164:165] op_sel_hi:[1,0]
	v_pk_mul_f32 v[12:13], v[164:165], v[12:13] op_sel_hi:[0,1]
	v_pk_mul_f32 v[4:5], v[4:5], v[64:65]
	v_pk_mul_f32 v[6:7], v[164:165], v[6:7] op_sel_hi:[0,1]
	v_pk_mul_f32 v[46:47], v[46:47], v[50:51]
	v_pk_mul_f32 v[12:13], v[12:13], v[68:69]
	v_pk_mul_f32 v[14:15], v[164:165], v[14:15] op_sel_hi:[0,1]
	v_pk_mul_f32 v[0:1], v[164:165], v[0:1] op_sel_hi:[0,1]
	v_pk_mul_f32 v[6:7], v[6:7], v[70:71]
	v_pk_mul_f32 v[50:51], v[4:5], v[72:73]
	v_pk_mul_f32 v[4:5], v[4:5], v[74:75]
	s_add_u32 s4, s94, s4
	v_pk_mul_f32 v[8:9], v[164:165], v[8:9] op_sel_hi:[0,1]
	v_pk_mul_f32 v[14:15], v[14:15], v[138:139]
	v_pk_mul_f32 v[0:1], v[0:1], v[66:67]
	v_pk_fma_f32 v[50:51], v[12:13], v[74:75], v[50:51] neg_lo:[0,0,1] neg_hi:[0,0,1]
	v_pk_fma_f32 v[4:5], v[12:13], v[72:73], v[4:5]
	v_pk_mul_f32 v[12:13], v[6:7], v[76:77]
	v_pk_mul_f32 v[6:7], v[6:7], v[78:79]
	s_addc_u32 s5, s95, 0
	s_lshl_b32 s2, s2, 9
	v_pk_mul_f32 v[16:17], v[164:165], v[16:17] op_sel_hi:[0,1]
	v_pk_mul_f32 v[18:19], v[164:165], v[18:19] op_sel_hi:[0,1]
	v_pk_mul_f32 v[8:9], v[8:9], v[136:137]
	v_pk_fma_f32 v[12:13], v[14:15], v[78:79], v[12:13] neg_lo:[0,0,1] neg_hi:[0,0,1]
	v_pk_fma_f32 v[6:7], v[14:15], v[76:77], v[6:7]
	v_pk_mul_f32 v[14:15], v[0:1], v[128:129]
	v_pk_mul_f32 v[0:1], v[0:1], v[130:131]
	s_and_b32 s2, s2, 0xe000
	v_pk_mul_f32 v[34:35], v[34:35], v[164:165] op_sel_hi:[1,0]
	v_pk_mul_f32 v[20:21], v[164:165], v[20:21] op_sel_hi:[0,1]
	v_pk_mul_f32 v[16:17], v[16:17], v[142:143]
	v_pk_mul_f32 v[18:19], v[18:19], v[140:141]
	v_pk_mul_f32 v[2:3], v[164:165], v[2:3] op_sel_hi:[0,1]
	v_pk_fma_f32 v[0:1], v[8:9], v[128:129], v[0:1]
	v_mov_b32_e32 v153, v169
	v_mov_b32_e32 v49, v169
	s_add_u32 s2, s58, s2
	v_pk_mul_f32 v[34:35], v[34:35], v[150:151]
	v_pk_mul_f32 v[20:21], v[20:21], v[60:61]
	v_pk_mul_f32 v[10:11], v[164:165], v[10:11] op_sel_hi:[0,1]
	v_pk_mul_f32 v[2:3], v[2:3], v[132:133]
	v_cvt_pk_bf16_f32 v142, v16, v17
	v_cvt_pk_bf16_f32 v143, v18, v19
	v_cvt_pk_bf16_f32 v150, v0, v1
	v_add_u32_e32 v17, s49, v173
	v_add_u32_e32 v18, s49, v174
	v_add3_u32 v19, s50, v172, v175
	v_mov_b32_e32 v0, s50
	v_lshl_add_u64 v[172:173], v[152:153], 1, s[4:5]
	v_lshl_add_u64 v[174:175], v[48:49], 1, s[4:5]
	s_addc_u32 s5, 0, 0
	v_pk_mul_f32 v[44:45], v[44:45], v[164:165] op_sel_hi:[1,0]
	v_pk_mul_f32 v[40:41], v[40:41], v[164:165] op_sel_hi:[1,0]
	v_pk_mul_f32 v[42:43], v[42:43], v[164:165] op_sel_hi:[1,0]
	v_pk_mul_f32 v[36:37], v[36:37], v[164:165] op_sel_hi:[1,0]
	v_pk_mul_f32 v[32:33], v[32:33], v[164:165] op_sel_hi:[1,0]
	v_pk_mul_f32 v[38:39], v[38:39], v[164:165] op_sel_hi:[1,0]
	v_pk_mul_f32 v[28:29], v[28:29], v[164:165] op_sel_hi:[1,0]
	v_pk_mul_f32 v[24:25], v[24:25], v[164:165] op_sel_hi:[1,0]
	v_pk_mul_f32 v[30:31], v[30:31], v[164:165] op_sel_hi:[1,0]
	v_pk_mul_f32 v[26:27], v[26:27], v[164:165] op_sel_hi:[1,0]
	v_pk_mul_f32 v[22:23], v[164:165], v[22:23] op_sel_hi:[0,1]
	v_pk_mul_f32 v[10:11], v[10:11], v[134:135]
	v_pk_fma_f32 v[14:15], v[8:9], v[130:131], v[14:15] neg_lo:[0,0,1] neg_hi:[0,0,1]
	v_pk_mul_f32 v[8:9], v[2:3], v[54:55]
	v_pk_mul_f32 v[2:3], v[2:3], v[56:57]
	v_cvt_pk_bf16_f32 v140, v20, v21
	v_mad_u32_u24 v20, v166, s47, v0
	v_mov_b32_e32 v0, s49
	s_add_u32 s4, s37, s2
	v_pk_mul_f32 v[44:45], v[44:45], v[162:163]
	v_pk_mul_f32 v[40:41], v[40:41], v[160:161]
	v_pk_mul_f32 v[42:43], v[42:43], v[158:159]
	v_pk_mul_f32 v[36:37], v[36:37], v[52:53]
	v_pk_mul_f32 v[32:33], v[32:33], v[156:157]
	v_pk_mul_f32 v[38:39], v[38:39], v[154:155]
	v_pk_mul_f32 v[28:29], v[28:29], v[148:149]
	v_pk_mul_f32 v[24:25], v[24:25], v[146:147]
	v_pk_mul_f32 v[30:31], v[30:31], v[58:59]
	v_pk_mul_f32 v[26:27], v[26:27], v[144:145]
	v_pk_mul_f32 v[22:23], v[22:23], v[62:63]
	v_pk_fma_f32 v[8:9], v[10:11], v[56:57], v[8:9] neg_lo:[0,0,1] neg_hi:[0,0,1]
	v_pk_fma_f32 v[2:3], v[10:11], v[54:55], v[2:3]
	v_cvt_pk_bf16_f32 v146, v14, v15
	v_lshl_add_u32 v16, v166, 6, v187
	v_mad_u32_u24 v21, v166, s46, v0
	v_add_u32_e32 v0, v165, v176
	v_mov_b32_e32 v1, v169
	s_addc_u32 s5, s38, s5
	v_mov_b32_e32 v14, v169
	v_mov_b32_e32 v15, v169
	v_cvt_pk_bf16_f32 v128, v44, v45
	v_cvt_pk_bf16_f32 v129, v46, v47
	v_cvt_pk_bf16_f32 v130, v40, v41
	v_cvt_pk_bf16_f32 v131, v42, v43
	v_cvt_pk_bf16_f32 v132, v36, v37
	v_cvt_pk_bf16_f32 v133, v38, v39
	v_cvt_pk_bf16_f32 v134, v32, v33
	v_cvt_pk_bf16_f32 v135, v34, v35
	v_cvt_pk_bf16_f32 v136, v28, v29
	v_cvt_pk_bf16_f32 v137, v30, v31
	v_cvt_pk_bf16_f32 v138, v24, v25
	v_cvt_pk_bf16_f32 v139, v26, v27
	v_cvt_pk_bf16_f32 v141, v22, v23
	v_cvt_pk_bf16_f32 v145, v12, v13
	v_cvt_pk_bf16_f32 v147, v8, v9
	v_cvt_pk_bf16_f32 v148, v4, v5
	v_cvt_pk_bf16_f32 v149, v6, v7
	v_cvt_pk_bf16_f32 v151, v2, v3
	v_lshl_add_u64 v[176:177], v[0:1], 1, s[4:5]
	v_mov_b32_e32 v0, v169
	v_mov_b32_e32 v2, v169
	v_mov_b32_e32 v3, v169
	v_mov_b32_e32 v4, v169
	v_mov_b32_e32 v5, v169
	v_mov_b32_e32 v6, v169
	v_mov_b32_e32 v7, v169
	v_mov_b32_e32 v8, v169
	v_mov_b32_e32 v9, v169
	v_mov_b32_e32 v10, v169
	v_mov_b32_e32 v11, v169
	v_mov_b32_e32 v12, v169
	v_mov_b32_e32 v13, v169
	v_add_u32_e32 v191, v17, v171
	v_add_u32_e32 v192, v18, v183
	v_add_u32_e32 v193, v19, v167
	v_add_u32_e32 v194, v21, v170
	v_add_u32_e32 v195, v16, v170
	v_add_u32_e32 v197, v20, v170
	v_mov_b64_e32 v[30:31], v[14:15]
	v_mov_b64_e32 v[46:47], v[14:15]
	s_mov_b32 s57, 0
	v_cvt_pk_bf16_f32 v144, v50, v51
	v_mov_b32_e32 v190, 0
	v_mov_b64_e32 v[28:29], v[12:13]
	v_mov_b64_e32 v[26:27], v[10:11]
	v_mov_b64_e32 v[24:25], v[8:9]
	v_mov_b64_e32 v[22:23], v[6:7]
	v_mov_b64_e32 v[20:21], v[4:5]
	v_mov_b64_e32 v[18:19], v[2:3]
	v_mov_b64_e32 v[16:17], v[0:1]
	v_mov_b32_e32 v196, 0
	v_mov_b64_e32 v[44:45], v[12:13]
	v_mov_b64_e32 v[42:43], v[10:11]
	v_mov_b64_e32 v[40:41], v[8:9]
	v_mov_b64_e32 v[38:39], v[6:7]
	v_mov_b64_e32 v[36:37], v[4:5]
	v_mov_b64_e32 v[34:35], v[2:3]
	v_mov_b64_e32 v[32:33], v[0:1]
	s_branch .LBB0_1664

.LBB0_1725:
	ds_write_b128 v49, v[232:235] offset:22528
	s_or_b64 exec, exec, s[4:5]
	s_and_saveexec_b64 s[4:5], vcc
	s_xor_b64 s[4:5], exec, s[4:5]
	s_cbranch_execz .LBB0_1659

; __global__ void __launch_bounds__(512, 2) fwd_kernel(Params P) {
	.amdhsa_kernel _Z10fwd_kernel6Params
		.amdhsa_group_segment_fixed_size 0
		.amdhsa_private_segment_fixed_size 0
		.amdhsa_kernarg_size 536
		.amdhsa_user_sgpr_count 2
		.amdhsa_user_sgpr_dispatch_ptr 0
		.amdhsa_user_sgpr_queue_ptr 0
		.amdhsa_user_sgpr_kernarg_segment_ptr 1
		.amdhsa_user_sgpr_dispatch_id 0
		.amdhsa_user_sgpr_kernarg_preload_length 0
		.amdhsa_user_sgpr_kernarg_preload_offset 0
		.amdhsa_user_sgpr_private_segment_size 0
		.amdhsa_uses_dynamic_stack 0
		.amdhsa_enable_private_segment 0
		.amdhsa_system_sgpr_workgroup_id_x 1
		.amdhsa_system_sgpr_workgroup_id_y 0
		.amdhsa_system_sgpr_workgroup_id_z 0
		.amdhsa_system_sgpr_workgroup_info 0
		.amdhsa_system_vgpr_workitem_id 2
		.amdhsa_next_free_vgpr 255
		.amdhsa_next_free_sgpr 102
		.amdhsa_accum_offset 256
		.amdhsa_reserve_vcc 1
		.amdhsa_float_round_mode_32 0
		.amdhsa_float_round_mode_16_64 0
		.amdhsa_float_denorm_mode_32 3
		.amdhsa_float_denorm_mode_16_64 3
		.amdhsa_dx10_clamp 1
		.amdhsa_ieee_mode 1
		.amdhsa_fp16_overflow 0
		.amdhsa_tg_split 0
		.amdhsa_exception_fp_ieee_invalid_op 0
		.amdhsa_exception_fp_denorm_src 0
		.amdhsa_exception_fp_ieee_div_zero 0
		.amdhsa_exception_fp_ieee_overflow 0
		.amdhsa_exception_fp_ieee_underflow 0
		.amdhsa_exception_fp_ieee_inexact 0
		.amdhsa_exception_int_div_zero 0
	.end_amdhsa_kernel

; __global__ void __launch_bounds__(512, 2) fwd_kernel(Params P) {
amdhsa.kernels:
  - .agpr_count:     0
    .args:
      - .offset:         0
        .size:           280
        .value_kind:     by_value
      - .offset:         280
        .size:           4
        .value_kind:     hidden_block_count_x
      - .offset:         284
        .size:           4
        .value_kind:     hidden_block_count_y
      - .offset:         288
        .size:           4
        .value_kind:     hidden_block_count_z
      - .offset:         292
        .size:           2
        .value_kind:     hidden_group_size_x
      - .offset:         294
        .size:           2
        .value_kind:     hidden_group_size_y
      - .offset:         296
        .size:           2
        .value_kind:     hidden_group_size_z
      - .offset:         298
        .size:           2
        .value_kind:     hidden_remainder_x
      - .offset:         300
        .size:           2
        .value_kind:     hidden_remainder_y
      - .offset:         302
        .size:           2
        .value_kind:     hidden_remainder_z
      - .offset:         320
        .size:           8
        .value_kind:     hidden_global_offset_x
      - .offset:         328
        .size:           8
        .value_kind:     hidden_global_offset_y
      - .offset:         336
        .size:           8
        .value_kind:     hidden_global_offset_z
      - .offset:         344
        .size:           2
        .value_kind:     hidden_grid_dims
      - .offset:         368
        .size:           8
        .value_kind:     hidden_multigrid_sync_arg
      - .offset:         400
        .size:           4
        .value_kind:     hidden_dynamic_lds_size
    .group_segment_fixed_size: 0
    .kernarg_segment_align: 8
    .kernarg_segment_size: 536
    .language:       OpenCL C
    .language_version:
      - 2
      - 0
    .max_flat_workgroup_size: 512
    .name:           _Z10fwd_kernel6Params
    .private_segment_fixed_size: 0
    .sgpr_count:     108
    .sgpr_spill_count: 26
    .symbol:         _Z10fwd_kernel6Params.kd
    .uniform_work_group_size: 1
    .uses_dynamic_stack: false
    .vgpr_count:     255
    .vgpr_spill_count: 0
    .wavefront_size: 64
